# G1A/G1B projection epilogues: 8 row-sum loads hoisted to the top, per-block vmcnt(0) waits removed
# speedup vs baseline: 1.0229x; 1.0077x over previous
.LBB0_75:
	v_lshl_add_u32 v142, s47, 8, v184
	v_ashrrev_i32_e32 v143, 31, v142
	v_lshl_add_u64 v[144:145], v[142:143], 2, s[4:5]
	global_load_dword v208, v[144:145], off
	global_load_dword v209, v[144:145], off offset:64
	global_load_dword v210, v[144:145], off offset:128
	global_load_dword v211, v[144:145], off offset:192
	global_load_dword v212, v[144:145], off offset:512
	global_load_dword v213, v[144:145], off offset:576
	global_load_dword v214, v[144:145], off offset:640
	global_load_dword v215, v[144:145], off offset:704
	s_mul_hi_i32 s12, s46, 0x55555556
	s_lshr_b32 s13, s12, 31
	s_add_i32 s12, s12, s13
	s_mul_i32 s12, s12, 3
	s_sub_i32 s12, s46, s12
	v_lshl_or_b32 v2, s12, 8, v186
	s_add_i32 s12, s46, -6
	s_cmp_gt_u32 s12, 2
	s_cselect_b64 s[14:15], -1, 0
	s_add_i32 s12, s46, 2
	s_cmp_lt_u32 s12, 5
	s_cselect_b64 s[12:13], -1, 0
	s_and_b64 vcc, exec, s[14:15]
	s_mov_b32 s24, 0xbf3a00e3
	s_mov_b64 s[96:97], s[68:69]
	s_waitcnt vmcnt(0)
	v_fmamk_f32 v146, v208, 0x3a800000, v195
	v_rsq_f32_e32 v148, v146
	v_mad_i64_i32 v[146:147], s[44:45], v142, s95, 0
	s_mov_b64 s[44:45], -1
	v_pk_mul_f32 v[152:153], v[130:131], v[148:149] op_sel_hi:[1,0]
	v_pk_mul_f32 v[154:155], v[128:129], v[148:149] op_sel_hi:[1,0]
	v_pk_mul_f32 v[130:131], v[126:127], v[148:149] op_sel_hi:[1,0]
	v_pk_mul_f32 v[150:151], v[124:125], v[148:149] op_sel_hi:[1,0]
	v_ashrrev_i32_e32 v125, 31, v2
	s_cbranch_vccz .LBB0_77
	v_and_b32_e32 v127, 0x7fffffff, v155
	v_and_b32_e32 v126, 0x7fffffff, v154
	v_pk_fma_f32 v[126:127], v[126:127], s[52:53], 1.0 op_sel_hi:[1,0,0]
	v_mov_b64_e32 v[128:129], s[24:25]
	v_rcp_f32_e32 v126, v126
	v_rcp_f32_e32 v127, v127
	v_pk_mul_f32 v[174:175], v[154:155], v[154:155]
	v_and_b32_e32 v177, 0x7fffffff, v153
	v_and_b32_e32 v176, 0x7fffffff, v152
	v_pk_fma_f32 v[172:173], v[126:127], s[62:63], v[128:129] op_sel_hi:[1,0,0]
	v_pk_mul_f32 v[174:175], v[174:175], s[86:87] op_sel_hi:[1,0]
	v_pk_fma_f32 v[176:177], v[176:177], s[52:53], 1.0 op_sel_hi:[1,0,0]
	v_pk_fma_f32 v[172:173], v[126:127], v[172:173], s[30:31] op_sel_hi:[1,1,0]
	v_exp_f32_e32 v174, v174
	v_exp_f32_e32 v175, v175
	v_rcp_f32_e32 v176, v176
	v_rcp_f32_e32 v177, v177
	v_pk_fma_f32 v[172:173], v[126:127], v[172:173], s[94:95] op_sel_hi:[1,1,0]
	v_pk_mul_f32 v[182:183], v[150:151], v[150:151]
	v_pk_fma_f32 v[172:173], v[126:127], v[172:173], s[84:85] op_sel_hi:[1,1,0]
	v_pk_mul_f32 v[182:183], v[182:183], s[86:87] op_sel_hi:[1,0]
	v_pk_mul_f32 v[126:127], v[126:127], v[172:173]
	v_pk_mul_f32 v[172:173], v[152:153], v[152:153]
	v_pk_mul_f32 v[126:127], v[174:175], v[126:127]
	v_pk_fma_f32 v[174:175], v[176:177], s[62:63], v[128:129] op_sel_hi:[1,0,0]
	v_pk_mul_f32 v[172:173], v[172:173], s[86:87] op_sel_hi:[1,0]
	v_pk_fma_f32 v[174:175], v[176:177], v[174:175], s[30:31] op_sel_hi:[1,1,0]
	v_exp_f32_e32 v172, v172
	v_pk_fma_f32 v[174:175], v[176:177], v[174:175], s[94:95] op_sel_hi:[1,1,0]
	v_exp_f32_e32 v173, v173
	v_pk_fma_f32 v[174:175], v[176:177], v[174:175], s[84:85] op_sel_hi:[1,1,0]
	v_and_b32_e32 v189, 0x7fffffff, v131
	v_pk_mul_f32 v[174:175], v[176:177], v[174:175]
	v_and_b32_e32 v177, 0x7fffffff, v151
	v_and_b32_e32 v176, 0x7fffffff, v150
	v_pk_fma_f32 v[176:177], v[176:177], s[52:53], 1.0 op_sel_hi:[1,0,0]
	v_pk_mul_f32 v[172:173], v[172:173], v[174:175]
	v_rcp_f32_e32 v176, v176
	v_rcp_f32_e32 v177, v177
	v_and_b32_e32 v188, 0x7fffffff, v130
	v_exp_f32_e32 v182, v182
	v_exp_f32_e32 v183, v183
	v_pk_fma_f32 v[174:175], v[176:177], s[62:63], v[128:129] op_sel_hi:[1,0,0]
	v_pk_fma_f32 v[188:189], v[188:189], s[52:53], 1.0 op_sel_hi:[1,0,0]
	v_pk_fma_f32 v[174:175], v[176:177], v[174:175], s[30:31] op_sel_hi:[1,1,0]
	v_rcp_f32_e32 v188, v188
	v_pk_fma_f32 v[174:175], v[176:177], v[174:175], s[94:95] op_sel_hi:[1,1,0]
	v_rcp_f32_e32 v189, v189
	v_pk_fma_f32 v[174:175], v[176:177], v[174:175], s[84:85] op_sel_hi:[1,1,0]
	v_cmp_gt_f32_e32 vcc, 0, v150
	v_pk_mul_f32 v[174:175], v[176:177], v[174:175]
	v_pk_mul_f32 v[176:177], v[130:131], v[130:131]
	v_pk_mul_f32 v[174:175], v[182:183], v[174:175]
	v_pk_fma_f32 v[128:129], v[188:189], s[62:63], v[128:129] op_sel_hi:[1,0,0]
	v_pk_mul_f32 v[182:183], v[150:151], v[174:175]
	v_pk_fma_f32 v[190:191], v[150:151], v[174:175], v[150:151] neg_lo:[1,0,0] neg_hi:[1,0,0]
	v_pk_mul_f32 v[174:175], v[176:177], s[86:87] op_sel_hi:[1,0]
	v_pk_fma_f32 v[128:129], v[188:189], v[128:129], s[30:31] op_sel_hi:[1,1,0]
	v_exp_f32_e32 v174, v174
	v_exp_f32_e32 v175, v175
	v_pk_fma_f32 v[128:129], v[188:189], v[128:129], s[94:95] op_sel_hi:[1,1,0]
	v_pk_mul_f32 v[178:179], v[154:155], v[126:127]
	v_pk_fma_f32 v[126:127], v[154:155], v[126:127], v[154:155] neg_lo:[1,0,0] neg_hi:[1,0,0]
	v_pk_fma_f32 v[128:129], v[188:189], v[128:129], s[84:85] op_sel_hi:[1,1,0]
	v_cndmask_b32_e32 v193, v190, v182, vcc
	v_cmp_gt_f32_e32 vcc, 0, v154
	v_pk_mul_f32 v[128:129], v[188:189], v[128:129]
	v_pk_mul_f32 v[180:181], v[152:153], v[172:173]
	v_cndmask_b32_e32 v192, v126, v178, vcc
	v_cmp_gt_f32_e32 vcc, 0, v151
	v_pk_mul_f32 v[128:129], v[174:175], v[128:129]
	v_pk_fma_f32 v[172:173], v[152:153], v[172:173], v[152:153] neg_lo:[1,0,0] neg_hi:[1,0,0]
	v_cndmask_b32_e32 v177, v191, v183, vcc
	v_cmp_gt_f32_e32 vcc, 0, v155
	v_pk_mul_f32 v[188:189], v[130:131], v[128:129]
	v_pk_fma_f32 v[128:129], v[130:131], v[128:129], v[130:131] neg_lo:[1,0,0] neg_hi:[1,0,0]
	v_cndmask_b32_e32 v176, v127, v179, vcc
	v_cmp_gt_f32_e32 vcc, 0, v130
	v_pk_add_f32 v[126:127], v[192:193], v[176:177]
	s_and_b64 s[44:45], s[12:13], exec
	v_cndmask_b32_e32 v191, v128, v188, vcc
	v_cmp_gt_f32_e32 vcc, 0, v152
	s_cselect_b32 s45, s64, s76
	s_cselect_b32 s44, s63, s65
	v_cndmask_b32_e32 v190, v172, v180, vcc
	v_cmp_gt_f32_e32 vcc, 0, v131
	v_lshl_add_u64 v[174:175], s[44:45], 0, v[146:147]
	v_mov_b32_e32 v124, v2
	v_cndmask_b32_e32 v179, v129, v189, vcc
	v_cmp_gt_f32_e32 vcc, 0, v153
	v_lshl_add_u64 v[174:175], v[124:125], 1, v[174:175]
	s_mov_b64 s[44:45], 0
	v_cndmask_b32_e32 v178, v173, v181, vcc
	v_pk_add_f32 v[128:129], v[190:191], v[178:179]
	v_pk_mul_f32 v[172:173], v[178:179], v[178:179]
	v_pk_add_f32 v[128:129], v[126:127], v[128:129]
	v_pk_mul_f32 v[126:127], v[176:177], v[176:177]
	v_pk_fma_f32 v[172:173], v[190:191], v[190:191], v[172:173]
	v_pk_fma_f32 v[126:127], v[192:193], v[192:193], v[126:127]
	v_add_f32_e32 v128, v128, v129
	v_pk_add_f32 v[126:127], v[126:127], v[172:173]
	v_mov_b32_e32 v181, v178
	v_add_f32_e32 v126, v126, v127
	v_mov_b32_e32 v180, v190
	v_mov_b32_e32 v183, v176
	v_mov_b32_e32 v182, v192
	v_mov_b32_e32 v178, v191
	v_mov_b32_e32 v176, v193

.LBB0_87:
	s_nop 0
	v_or_b32_e32 v116, 16, v142
	s_waitcnt lgkmcnt(0)
	v_mad_i64_i32 v[118:119], s[14:15], v116, s95, 0
	s_and_b64 vcc, exec, s[44:45]
	s_mov_b64 s[14:15], -1
	v_fmamk_f32 v117, v209, 0x3a800000, v195
	v_rsq_f32_e32 v120, v117
	s_nop 0
	v_pk_mul_f32 v[126:127], v[114:115], v[120:121] op_sel_hi:[1,0]
	v_pk_mul_f32 v[128:129], v[112:113], v[120:121] op_sel_hi:[1,0]
	v_pk_mul_f32 v[114:115], v[110:111], v[120:121] op_sel_hi:[1,0]
	v_pk_mul_f32 v[122:123], v[108:109], v[120:121] op_sel_hi:[1,0]
	s_cbranch_vccnz .LBB0_89
	v_and_b32_e32 v109, 0x7fffffff, v129
	v_and_b32_e32 v108, 0x7fffffff, v128
	v_pk_fma_f32 v[108:109], v[108:109], s[52:53], 1.0 op_sel_hi:[1,0,0]
	v_mov_b64_e32 v[110:111], s[24:25]
	v_rcp_f32_e32 v108, v108
	v_rcp_f32_e32 v109, v109
	v_pk_mul_f32 v[130:131], v[128:129], v[128:129]
	v_and_b32_e32 v147, 0x7fffffff, v127
	v_and_b32_e32 v146, 0x7fffffff, v126
	v_pk_fma_f32 v[112:113], v[108:109], s[62:63], v[110:111] op_sel_hi:[1,0,0]
	v_pk_mul_f32 v[130:131], v[130:131], s[86:87] op_sel_hi:[1,0]
	v_pk_fma_f32 v[146:147], v[146:147], s[52:53], 1.0 op_sel_hi:[1,0,0]
	v_pk_fma_f32 v[112:113], v[108:109], v[112:113], s[30:31] op_sel_hi:[1,1,0]
	v_exp_f32_e32 v130, v130
	v_exp_f32_e32 v131, v131
	v_rcp_f32_e32 v146, v146
	v_rcp_f32_e32 v147, v147
	v_pk_fma_f32 v[112:113], v[108:109], v[112:113], s[94:95] op_sel_hi:[1,1,0]
	v_pk_mul_f32 v[148:149], v[122:123], v[122:123]
	v_pk_fma_f32 v[112:113], v[108:109], v[112:113], s[84:85] op_sel_hi:[1,1,0]
	v_pk_mul_f32 v[148:149], v[148:149], s[86:87] op_sel_hi:[1,0]
	v_pk_mul_f32 v[108:109], v[108:109], v[112:113]
	v_pk_mul_f32 v[112:113], v[126:127], v[126:127]
	v_pk_mul_f32 v[108:109], v[130:131], v[108:109]
	v_pk_fma_f32 v[130:131], v[146:147], s[62:63], v[110:111] op_sel_hi:[1,0,0]
	v_pk_mul_f32 v[112:113], v[112:113], s[86:87] op_sel_hi:[1,0]
	v_pk_fma_f32 v[130:131], v[146:147], v[130:131], s[30:31] op_sel_hi:[1,1,0]
	v_exp_f32_e32 v112, v112
	v_pk_fma_f32 v[130:131], v[146:147], v[130:131], s[94:95] op_sel_hi:[1,1,0]
	v_exp_f32_e32 v113, v113
	v_pk_fma_f32 v[130:131], v[146:147], v[130:131], s[84:85] op_sel_hi:[1,1,0]
	v_and_b32_e32 v153, 0x7fffffff, v115
	v_pk_mul_f32 v[130:131], v[146:147], v[130:131]
	v_and_b32_e32 v147, 0x7fffffff, v123
	v_and_b32_e32 v146, 0x7fffffff, v122
	v_pk_fma_f32 v[146:147], v[146:147], s[52:53], 1.0 op_sel_hi:[1,0,0]
	v_pk_mul_f32 v[112:113], v[112:113], v[130:131]
	v_rcp_f32_e32 v146, v146
	v_rcp_f32_e32 v147, v147
	v_and_b32_e32 v152, 0x7fffffff, v114
	v_exp_f32_e32 v148, v148
	v_exp_f32_e32 v149, v149
	v_pk_fma_f32 v[130:131], v[146:147], s[62:63], v[110:111] op_sel_hi:[1,0,0]
	v_pk_fma_f32 v[152:153], v[152:153], s[52:53], 1.0 op_sel_hi:[1,0,0]
	v_pk_fma_f32 v[130:131], v[146:147], v[130:131], s[30:31] op_sel_hi:[1,1,0]
	v_rcp_f32_e32 v152, v152
	v_pk_fma_f32 v[130:131], v[146:147], v[130:131], s[94:95] op_sel_hi:[1,1,0]
	v_rcp_f32_e32 v153, v153
	v_pk_fma_f32 v[130:131], v[146:147], v[130:131], s[84:85] op_sel_hi:[1,1,0]
	v_cmp_gt_f32_e32 vcc, 0, v122
	v_pk_mul_f32 v[130:131], v[146:147], v[130:131]
	v_pk_mul_f32 v[146:147], v[114:115], v[114:115]
	v_pk_mul_f32 v[130:131], v[148:149], v[130:131]
	v_pk_fma_f32 v[110:111], v[152:153], s[62:63], v[110:111] op_sel_hi:[1,0,0]
	v_pk_mul_f32 v[172:173], v[122:123], v[130:131]
	v_pk_fma_f32 v[174:175], v[122:123], v[130:131], v[122:123] neg_lo:[1,0,0] neg_hi:[1,0,0]
	v_pk_mul_f32 v[130:131], v[146:147], s[86:87] op_sel_hi:[1,0]
	v_pk_fma_f32 v[110:111], v[152:153], v[110:111], s[30:31] op_sel_hi:[1,1,0]
	v_exp_f32_e32 v130, v130
	v_exp_f32_e32 v131, v131
	v_pk_fma_f32 v[110:111], v[152:153], v[110:111], s[94:95] op_sel_hi:[1,1,0]
	v_pk_mul_f32 v[150:151], v[128:129], v[108:109]
	v_pk_fma_f32 v[108:109], v[128:129], v[108:109], v[128:129] neg_lo:[1,0,0] neg_hi:[1,0,0]
	v_pk_fma_f32 v[110:111], v[152:153], v[110:111], s[84:85] op_sel_hi:[1,1,0]
	v_cndmask_b32_e32 v149, v174, v172, vcc
	v_cmp_gt_f32_e32 vcc, 0, v128
	v_pk_mul_f32 v[110:111], v[152:153], v[110:111]
	v_pk_mul_f32 v[154:155], v[126:127], v[112:113]
	v_cndmask_b32_e32 v148, v108, v150, vcc
	v_cmp_gt_f32_e32 vcc, 0, v123
	v_pk_mul_f32 v[110:111], v[130:131], v[110:111]
	v_pk_fma_f32 v[112:113], v[126:127], v[112:113], v[126:127] neg_lo:[1,0,0] neg_hi:[1,0,0]
	v_cndmask_b32_e32 v147, v175, v173, vcc
	v_cmp_gt_f32_e32 vcc, 0, v129
	v_pk_mul_f32 v[176:177], v[114:115], v[110:111]
	v_pk_fma_f32 v[110:111], v[114:115], v[110:111], v[114:115] neg_lo:[1,0,0] neg_hi:[1,0,0]
	v_cndmask_b32_e32 v146, v109, v151, vcc
	v_cmp_gt_f32_e32 vcc, 0, v114
	v_pk_add_f32 v[108:109], v[148:149], v[146:147]
	s_and_b64 s[14:15], s[12:13], exec
	v_cndmask_b32_e32 v153, v110, v176, vcc
	v_cmp_gt_f32_e32 vcc, 0, v126
	s_cselect_b32 s15, s64, s76
	s_cselect_b32 s14, s63, s65
	v_cndmask_b32_e32 v152, v112, v154, vcc
	v_cmp_gt_f32_e32 vcc, 0, v115
	v_lshl_add_u64 v[130:131], s[14:15], 0, v[118:119]
	v_mov_b32_e32 v124, v2
	v_cndmask_b32_e32 v151, v111, v177, vcc
	v_cmp_gt_f32_e32 vcc, 0, v127
	v_lshl_add_u64 v[130:131], v[124:125], 1, v[130:131]
	s_mov_b64 s[14:15], 0
	v_cndmask_b32_e32 v150, v113, v155, vcc
	v_pk_add_f32 v[110:111], v[152:153], v[150:151]
	v_pk_mul_f32 v[112:113], v[150:151], v[150:151]
	v_pk_add_f32 v[110:111], v[108:109], v[110:111]
	v_pk_mul_f32 v[108:109], v[146:147], v[146:147]
	v_pk_fma_f32 v[112:113], v[152:153], v[152:153], v[112:113]
	v_pk_fma_f32 v[108:109], v[148:149], v[148:149], v[108:109]
	v_add_f32_e32 v110, v110, v111
	v_pk_add_f32 v[108:109], v[108:109], v[112:113]
	s_nop 0
	v_add_f32_e32 v108, v108, v109

.LBB0_99:
	s_nop 0
	v_or_b32_e32 v100, 32, v142
	s_waitcnt lgkmcnt(0)
	v_mad_i64_i32 v[102:103], s[14:15], v100, s95, 0
	s_and_b64 vcc, exec, s[44:45]
	s_mov_b64 s[14:15], -1
	v_fmamk_f32 v101, v210, 0x3a800000, v195
	v_rsq_f32_e32 v104, v101
	s_nop 0
	v_pk_mul_f32 v[108:109], v[98:99], v[104:105] op_sel_hi:[1,0]
	v_pk_mul_f32 v[110:111], v[96:97], v[104:105] op_sel_hi:[1,0]
	v_pk_mul_f32 v[98:99], v[94:95], v[104:105] op_sel_hi:[1,0]
	v_pk_mul_f32 v[106:107], v[92:93], v[104:105] op_sel_hi:[1,0]
	s_cbranch_vccnz .LBB0_101
	v_and_b32_e32 v93, 0x7fffffff, v111
	v_and_b32_e32 v92, 0x7fffffff, v110
	v_pk_fma_f32 v[92:93], v[92:93], s[52:53], 1.0 op_sel_hi:[1,0,0]
	v_mov_b64_e32 v[94:95], s[24:25]
	v_rcp_f32_e32 v92, v92
	v_rcp_f32_e32 v93, v93
	v_pk_mul_f32 v[112:113], v[110:111], v[110:111]
	v_and_b32_e32 v115, 0x7fffffff, v109
	v_and_b32_e32 v114, 0x7fffffff, v108
	v_pk_fma_f32 v[96:97], v[92:93], s[62:63], v[94:95] op_sel_hi:[1,0,0]
	v_pk_mul_f32 v[112:113], v[112:113], s[86:87] op_sel_hi:[1,0]
	v_pk_fma_f32 v[114:115], v[114:115], s[52:53], 1.0 op_sel_hi:[1,0,0]
	v_pk_fma_f32 v[96:97], v[92:93], v[96:97], s[30:31] op_sel_hi:[1,1,0]
	v_exp_f32_e32 v112, v112
	v_exp_f32_e32 v113, v113
	v_rcp_f32_e32 v114, v114
	v_rcp_f32_e32 v115, v115
	v_pk_fma_f32 v[96:97], v[92:93], v[96:97], s[94:95] op_sel_hi:[1,1,0]
	v_pk_mul_f32 v[116:117], v[106:107], v[106:107]
	v_pk_fma_f32 v[96:97], v[92:93], v[96:97], s[84:85] op_sel_hi:[1,1,0]
	v_pk_mul_f32 v[116:117], v[116:117], s[86:87] op_sel_hi:[1,0]
	v_pk_mul_f32 v[92:93], v[92:93], v[96:97]
	v_pk_mul_f32 v[96:97], v[108:109], v[108:109]
	v_pk_mul_f32 v[92:93], v[112:113], v[92:93]
	v_pk_fma_f32 v[112:113], v[114:115], s[62:63], v[94:95] op_sel_hi:[1,0,0]
	v_pk_mul_f32 v[96:97], v[96:97], s[86:87] op_sel_hi:[1,0]
	v_pk_fma_f32 v[112:113], v[114:115], v[112:113], s[30:31] op_sel_hi:[1,1,0]
	v_exp_f32_e32 v96, v96
	v_pk_fma_f32 v[112:113], v[114:115], v[112:113], s[94:95] op_sel_hi:[1,1,0]
	v_exp_f32_e32 v97, v97
	v_pk_fma_f32 v[112:113], v[114:115], v[112:113], s[84:85] op_sel_hi:[1,1,0]
	v_and_b32_e32 v121, 0x7fffffff, v99
	v_pk_mul_f32 v[112:113], v[114:115], v[112:113]
	v_and_b32_e32 v115, 0x7fffffff, v107
	v_and_b32_e32 v114, 0x7fffffff, v106
	v_pk_fma_f32 v[114:115], v[114:115], s[52:53], 1.0 op_sel_hi:[1,0,0]
	v_pk_mul_f32 v[96:97], v[96:97], v[112:113]
	v_rcp_f32_e32 v114, v114
	v_rcp_f32_e32 v115, v115
	v_and_b32_e32 v120, 0x7fffffff, v98
	v_exp_f32_e32 v116, v116
	v_exp_f32_e32 v117, v117
	v_pk_fma_f32 v[112:113], v[114:115], s[62:63], v[94:95] op_sel_hi:[1,0,0]
	v_pk_fma_f32 v[120:121], v[120:121], s[52:53], 1.0 op_sel_hi:[1,0,0]
	v_pk_fma_f32 v[112:113], v[114:115], v[112:113], s[30:31] op_sel_hi:[1,1,0]
	v_rcp_f32_e32 v120, v120
	v_pk_fma_f32 v[112:113], v[114:115], v[112:113], s[94:95] op_sel_hi:[1,1,0]
	v_rcp_f32_e32 v121, v121
	v_pk_fma_f32 v[112:113], v[114:115], v[112:113], s[84:85] op_sel_hi:[1,1,0]
	v_cmp_gt_f32_e32 vcc, 0, v106
	v_pk_mul_f32 v[112:113], v[114:115], v[112:113]
	v_pk_mul_f32 v[114:115], v[98:99], v[98:99]
	v_pk_mul_f32 v[112:113], v[116:117], v[112:113]
	v_pk_fma_f32 v[94:95], v[120:121], s[62:63], v[94:95] op_sel_hi:[1,0,0]
	v_pk_mul_f32 v[126:127], v[106:107], v[112:113]
	v_pk_fma_f32 v[128:129], v[106:107], v[112:113], v[106:107] neg_lo:[1,0,0] neg_hi:[1,0,0]
	v_pk_mul_f32 v[112:113], v[114:115], s[86:87] op_sel_hi:[1,0]
	v_pk_fma_f32 v[94:95], v[120:121], v[94:95], s[30:31] op_sel_hi:[1,1,0]
	v_exp_f32_e32 v112, v112
	v_exp_f32_e32 v113, v113
	v_pk_fma_f32 v[94:95], v[120:121], v[94:95], s[94:95] op_sel_hi:[1,1,0]
	v_pk_mul_f32 v[118:119], v[110:111], v[92:93]
	v_pk_fma_f32 v[92:93], v[110:111], v[92:93], v[110:111] neg_lo:[1,0,0] neg_hi:[1,0,0]
	v_pk_fma_f32 v[94:95], v[120:121], v[94:95], s[84:85] op_sel_hi:[1,1,0]
	v_cndmask_b32_e32 v117, v128, v126, vcc
	v_cmp_gt_f32_e32 vcc, 0, v110
	v_pk_mul_f32 v[94:95], v[120:121], v[94:95]
	v_pk_mul_f32 v[122:123], v[108:109], v[96:97]
	v_cndmask_b32_e32 v116, v92, v118, vcc
	v_cmp_gt_f32_e32 vcc, 0, v107
	v_pk_mul_f32 v[94:95], v[112:113], v[94:95]
	v_pk_fma_f32 v[96:97], v[108:109], v[96:97], v[108:109] neg_lo:[1,0,0] neg_hi:[1,0,0]
	v_cndmask_b32_e32 v115, v129, v127, vcc
	v_cmp_gt_f32_e32 vcc, 0, v111
	v_pk_mul_f32 v[130:131], v[98:99], v[94:95]
	v_pk_fma_f32 v[94:95], v[98:99], v[94:95], v[98:99] neg_lo:[1,0,0] neg_hi:[1,0,0]
	v_cndmask_b32_e32 v114, v93, v119, vcc
	v_cmp_gt_f32_e32 vcc, 0, v98
	v_pk_add_f32 v[92:93], v[116:117], v[114:115]
	s_and_b64 s[14:15], s[12:13], exec
	v_cndmask_b32_e32 v121, v94, v130, vcc
	v_cmp_gt_f32_e32 vcc, 0, v108
	s_cselect_b32 s15, s64, s76
	s_cselect_b32 s14, s63, s65
	v_cndmask_b32_e32 v120, v96, v122, vcc
	v_cmp_gt_f32_e32 vcc, 0, v99
	v_lshl_add_u64 v[112:113], s[14:15], 0, v[102:103]
	v_mov_b32_e32 v124, v2
	v_cndmask_b32_e32 v119, v95, v131, vcc
	v_cmp_gt_f32_e32 vcc, 0, v109
	v_lshl_add_u64 v[112:113], v[124:125], 1, v[112:113]
	s_mov_b64 s[14:15], 0
	v_cndmask_b32_e32 v118, v97, v123, vcc
	v_pk_add_f32 v[94:95], v[120:121], v[118:119]
	v_pk_mul_f32 v[96:97], v[118:119], v[118:119]
	v_pk_add_f32 v[94:95], v[92:93], v[94:95]
	v_pk_mul_f32 v[92:93], v[114:115], v[114:115]
	v_pk_fma_f32 v[96:97], v[120:121], v[120:121], v[96:97]
	v_pk_fma_f32 v[92:93], v[116:117], v[116:117], v[92:93]
	v_add_f32_e32 v94, v94, v95
	v_pk_add_f32 v[92:93], v[92:93], v[96:97]
	s_nop 0
	v_add_f32_e32 v92, v92, v93

.LBB0_111:
	s_nop 0
	v_or_b32_e32 v84, 48, v142
	s_waitcnt lgkmcnt(0)
	v_mad_i64_i32 v[86:87], s[14:15], v84, s95, 0
	s_and_b64 vcc, exec, s[44:45]
	s_mov_b64 s[14:15], -1
	v_fmamk_f32 v85, v211, 0x3a800000, v195
	v_rsq_f32_e32 v88, v85
	s_nop 0
	v_pk_mul_f32 v[92:93], v[82:83], v[88:89] op_sel_hi:[1,0]
	v_pk_mul_f32 v[94:95], v[80:81], v[88:89] op_sel_hi:[1,0]
	v_pk_mul_f32 v[82:83], v[78:79], v[88:89] op_sel_hi:[1,0]
	v_pk_mul_f32 v[90:91], v[76:77], v[88:89] op_sel_hi:[1,0]
	s_cbranch_vccnz .LBB0_113
	v_and_b32_e32 v77, 0x7fffffff, v95
	v_and_b32_e32 v76, 0x7fffffff, v94
	v_pk_fma_f32 v[76:77], v[76:77], s[52:53], 1.0 op_sel_hi:[1,0,0]
	v_mov_b64_e32 v[78:79], s[24:25]
	v_rcp_f32_e32 v76, v76
	v_rcp_f32_e32 v77, v77
	v_pk_mul_f32 v[96:97], v[94:95], v[94:95]
	v_and_b32_e32 v99, 0x7fffffff, v93
	v_and_b32_e32 v98, 0x7fffffff, v92
	v_pk_fma_f32 v[80:81], v[76:77], s[62:63], v[78:79] op_sel_hi:[1,0,0]
	v_pk_mul_f32 v[96:97], v[96:97], s[86:87] op_sel_hi:[1,0]
	v_pk_fma_f32 v[98:99], v[98:99], s[52:53], 1.0 op_sel_hi:[1,0,0]
	v_pk_fma_f32 v[80:81], v[76:77], v[80:81], s[30:31] op_sel_hi:[1,1,0]
	v_exp_f32_e32 v96, v96
	v_exp_f32_e32 v97, v97
	v_rcp_f32_e32 v98, v98
	v_rcp_f32_e32 v99, v99
	v_pk_fma_f32 v[80:81], v[76:77], v[80:81], s[94:95] op_sel_hi:[1,1,0]
	v_pk_mul_f32 v[100:101], v[90:91], v[90:91]
	v_pk_fma_f32 v[80:81], v[76:77], v[80:81], s[84:85] op_sel_hi:[1,1,0]
	v_pk_mul_f32 v[100:101], v[100:101], s[86:87] op_sel_hi:[1,0]
	v_pk_mul_f32 v[76:77], v[76:77], v[80:81]
	v_pk_mul_f32 v[80:81], v[92:93], v[92:93]
	v_pk_mul_f32 v[76:77], v[96:97], v[76:77]
	v_pk_fma_f32 v[96:97], v[98:99], s[62:63], v[78:79] op_sel_hi:[1,0,0]
	v_pk_mul_f32 v[80:81], v[80:81], s[86:87] op_sel_hi:[1,0]
	v_pk_fma_f32 v[96:97], v[98:99], v[96:97], s[30:31] op_sel_hi:[1,1,0]
	v_exp_f32_e32 v80, v80
	v_pk_fma_f32 v[96:97], v[98:99], v[96:97], s[94:95] op_sel_hi:[1,1,0]
	v_exp_f32_e32 v81, v81
	v_pk_fma_f32 v[96:97], v[98:99], v[96:97], s[84:85] op_sel_hi:[1,1,0]
	v_and_b32_e32 v105, 0x7fffffff, v83
	v_pk_mul_f32 v[96:97], v[98:99], v[96:97]
	v_and_b32_e32 v99, 0x7fffffff, v91
	v_and_b32_e32 v98, 0x7fffffff, v90
	v_pk_fma_f32 v[98:99], v[98:99], s[52:53], 1.0 op_sel_hi:[1,0,0]
	v_pk_mul_f32 v[80:81], v[80:81], v[96:97]
	v_rcp_f32_e32 v98, v98
	v_rcp_f32_e32 v99, v99
	v_and_b32_e32 v104, 0x7fffffff, v82
	v_exp_f32_e32 v100, v100
	v_exp_f32_e32 v101, v101
	v_pk_fma_f32 v[96:97], v[98:99], s[62:63], v[78:79] op_sel_hi:[1,0,0]
	v_pk_fma_f32 v[104:105], v[104:105], s[52:53], 1.0 op_sel_hi:[1,0,0]
	v_pk_fma_f32 v[96:97], v[98:99], v[96:97], s[30:31] op_sel_hi:[1,1,0]
	v_rcp_f32_e32 v104, v104
	v_pk_fma_f32 v[96:97], v[98:99], v[96:97], s[94:95] op_sel_hi:[1,1,0]
	v_rcp_f32_e32 v105, v105
	v_pk_fma_f32 v[96:97], v[98:99], v[96:97], s[84:85] op_sel_hi:[1,1,0]
	v_cmp_gt_f32_e32 vcc, 0, v90
	v_pk_mul_f32 v[96:97], v[98:99], v[96:97]
	v_pk_mul_f32 v[98:99], v[82:83], v[82:83]
	v_pk_mul_f32 v[96:97], v[100:101], v[96:97]
	v_pk_fma_f32 v[78:79], v[104:105], s[62:63], v[78:79] op_sel_hi:[1,0,0]
	v_pk_mul_f32 v[108:109], v[90:91], v[96:97]
	v_pk_fma_f32 v[110:111], v[90:91], v[96:97], v[90:91] neg_lo:[1,0,0] neg_hi:[1,0,0]
	v_pk_mul_f32 v[96:97], v[98:99], s[86:87] op_sel_hi:[1,0]
	v_pk_fma_f32 v[78:79], v[104:105], v[78:79], s[30:31] op_sel_hi:[1,1,0]
	v_exp_f32_e32 v96, v96
	v_exp_f32_e32 v97, v97
	v_pk_fma_f32 v[78:79], v[104:105], v[78:79], s[94:95] op_sel_hi:[1,1,0]
	v_pk_mul_f32 v[102:103], v[94:95], v[76:77]
	v_pk_fma_f32 v[76:77], v[94:95], v[76:77], v[94:95] neg_lo:[1,0,0] neg_hi:[1,0,0]
	v_pk_fma_f32 v[78:79], v[104:105], v[78:79], s[84:85] op_sel_hi:[1,1,0]
	v_cndmask_b32_e32 v101, v110, v108, vcc
	v_cmp_gt_f32_e32 vcc, 0, v94
	v_pk_mul_f32 v[78:79], v[104:105], v[78:79]
	v_pk_mul_f32 v[106:107], v[92:93], v[80:81]
	v_cndmask_b32_e32 v100, v76, v102, vcc
	v_cmp_gt_f32_e32 vcc, 0, v91
	v_pk_mul_f32 v[78:79], v[96:97], v[78:79]
	v_pk_fma_f32 v[80:81], v[92:93], v[80:81], v[92:93] neg_lo:[1,0,0] neg_hi:[1,0,0]
	v_cndmask_b32_e32 v99, v111, v109, vcc
	v_cmp_gt_f32_e32 vcc, 0, v95
	v_pk_mul_f32 v[112:113], v[82:83], v[78:79]
	v_pk_fma_f32 v[78:79], v[82:83], v[78:79], v[82:83] neg_lo:[1,0,0] neg_hi:[1,0,0]
	v_cndmask_b32_e32 v98, v77, v103, vcc
	v_cmp_gt_f32_e32 vcc, 0, v82
	v_pk_add_f32 v[76:77], v[100:101], v[98:99]
	s_and_b64 s[14:15], s[12:13], exec
	v_cndmask_b32_e32 v105, v78, v112, vcc
	v_cmp_gt_f32_e32 vcc, 0, v92
	s_cselect_b32 s15, s64, s76
	s_cselect_b32 s14, s63, s65
	v_cndmask_b32_e32 v104, v80, v106, vcc
	v_cmp_gt_f32_e32 vcc, 0, v83
	v_lshl_add_u64 v[96:97], s[14:15], 0, v[86:87]
	v_mov_b32_e32 v124, v2
	v_cndmask_b32_e32 v103, v79, v113, vcc
	v_cmp_gt_f32_e32 vcc, 0, v93
	v_lshl_add_u64 v[96:97], v[124:125], 1, v[96:97]
	s_mov_b64 s[14:15], 0
	v_cndmask_b32_e32 v102, v81, v107, vcc
	v_pk_add_f32 v[78:79], v[104:105], v[102:103]
	v_pk_mul_f32 v[80:81], v[102:103], v[102:103]
	v_pk_add_f32 v[78:79], v[76:77], v[78:79]
	v_pk_mul_f32 v[76:77], v[98:99], v[98:99]
	v_pk_fma_f32 v[80:81], v[104:105], v[104:105], v[80:81]
	v_pk_fma_f32 v[76:77], v[100:101], v[100:101], v[76:77]
	v_add_f32_e32 v78, v78, v79
	v_pk_add_f32 v[76:77], v[76:77], v[80:81]
	s_nop 0
	v_add_f32_e32 v76, v76, v77

.LBB0_123:
	s_nop 0
	v_add_u32_e32 v68, 0x80, v142
	s_waitcnt lgkmcnt(0)
	v_mad_i64_i32 v[70:71], s[14:15], v68, s95, 0
	s_and_b64 vcc, exec, s[44:45]
	s_mov_b64 s[14:15], -1
	v_fmamk_f32 v69, v212, 0x3a800000, v195
	v_rsq_f32_e32 v72, v69
	s_nop 0
	v_pk_mul_f32 v[76:77], v[66:67], v[72:73] op_sel_hi:[1,0]
	v_pk_mul_f32 v[78:79], v[64:65], v[72:73] op_sel_hi:[1,0]
	v_pk_mul_f32 v[66:67], v[62:63], v[72:73] op_sel_hi:[1,0]
	v_pk_mul_f32 v[74:75], v[60:61], v[72:73] op_sel_hi:[1,0]
	s_cbranch_vccnz .LBB0_125
	v_and_b32_e32 v61, 0x7fffffff, v79
	v_and_b32_e32 v60, 0x7fffffff, v78
	v_pk_fma_f32 v[60:61], v[60:61], s[52:53], 1.0 op_sel_hi:[1,0,0]
	v_mov_b64_e32 v[62:63], s[24:25]
	v_rcp_f32_e32 v60, v60
	v_rcp_f32_e32 v61, v61
	v_pk_mul_f32 v[80:81], v[78:79], v[78:79]
	v_and_b32_e32 v83, 0x7fffffff, v77
	v_and_b32_e32 v82, 0x7fffffff, v76
	v_pk_fma_f32 v[64:65], v[60:61], s[62:63], v[62:63] op_sel_hi:[1,0,0]
	v_pk_mul_f32 v[80:81], v[80:81], s[86:87] op_sel_hi:[1,0]
	v_pk_fma_f32 v[82:83], v[82:83], s[52:53], 1.0 op_sel_hi:[1,0,0]
	v_pk_fma_f32 v[64:65], v[60:61], v[64:65], s[30:31] op_sel_hi:[1,1,0]
	v_exp_f32_e32 v80, v80
	v_exp_f32_e32 v81, v81
	v_rcp_f32_e32 v82, v82
	v_rcp_f32_e32 v83, v83
	v_pk_fma_f32 v[64:65], v[60:61], v[64:65], s[94:95] op_sel_hi:[1,1,0]
	v_pk_mul_f32 v[84:85], v[74:75], v[74:75]
	v_pk_fma_f32 v[64:65], v[60:61], v[64:65], s[84:85] op_sel_hi:[1,1,0]
	v_pk_mul_f32 v[84:85], v[84:85], s[86:87] op_sel_hi:[1,0]
	v_pk_mul_f32 v[60:61], v[60:61], v[64:65]
	v_pk_mul_f32 v[64:65], v[76:77], v[76:77]
	v_pk_mul_f32 v[60:61], v[80:81], v[60:61]
	v_pk_fma_f32 v[80:81], v[82:83], s[62:63], v[62:63] op_sel_hi:[1,0,0]
	v_pk_mul_f32 v[64:65], v[64:65], s[86:87] op_sel_hi:[1,0]
	v_pk_fma_f32 v[80:81], v[82:83], v[80:81], s[30:31] op_sel_hi:[1,1,0]
	v_exp_f32_e32 v64, v64
	v_pk_fma_f32 v[80:81], v[82:83], v[80:81], s[94:95] op_sel_hi:[1,1,0]
	v_exp_f32_e32 v65, v65
	v_pk_fma_f32 v[80:81], v[82:83], v[80:81], s[84:85] op_sel_hi:[1,1,0]
	v_and_b32_e32 v89, 0x7fffffff, v67
	v_pk_mul_f32 v[80:81], v[82:83], v[80:81]
	v_and_b32_e32 v83, 0x7fffffff, v75
	v_and_b32_e32 v82, 0x7fffffff, v74
	v_pk_fma_f32 v[82:83], v[82:83], s[52:53], 1.0 op_sel_hi:[1,0,0]
	v_pk_mul_f32 v[64:65], v[64:65], v[80:81]
	v_rcp_f32_e32 v82, v82
	v_rcp_f32_e32 v83, v83
	v_and_b32_e32 v88, 0x7fffffff, v66
	v_exp_f32_e32 v84, v84
	v_exp_f32_e32 v85, v85
	v_pk_fma_f32 v[80:81], v[82:83], s[62:63], v[62:63] op_sel_hi:[1,0,0]
	v_pk_fma_f32 v[88:89], v[88:89], s[52:53], 1.0 op_sel_hi:[1,0,0]
	v_pk_fma_f32 v[80:81], v[82:83], v[80:81], s[30:31] op_sel_hi:[1,1,0]
	v_rcp_f32_e32 v88, v88
	v_pk_fma_f32 v[80:81], v[82:83], v[80:81], s[94:95] op_sel_hi:[1,1,0]
	v_rcp_f32_e32 v89, v89
	v_pk_fma_f32 v[80:81], v[82:83], v[80:81], s[84:85] op_sel_hi:[1,1,0]
	v_cmp_gt_f32_e32 vcc, 0, v74
	v_pk_mul_f32 v[80:81], v[82:83], v[80:81]
	v_pk_mul_f32 v[82:83], v[66:67], v[66:67]
	v_pk_mul_f32 v[80:81], v[84:85], v[80:81]
	v_pk_fma_f32 v[62:63], v[88:89], s[62:63], v[62:63] op_sel_hi:[1,0,0]
	v_pk_mul_f32 v[92:93], v[74:75], v[80:81]
	v_pk_fma_f32 v[94:95], v[74:75], v[80:81], v[74:75] neg_lo:[1,0,0] neg_hi:[1,0,0]
	v_pk_mul_f32 v[80:81], v[82:83], s[86:87] op_sel_hi:[1,0]
	v_pk_fma_f32 v[62:63], v[88:89], v[62:63], s[30:31] op_sel_hi:[1,1,0]
	v_exp_f32_e32 v80, v80
	v_exp_f32_e32 v81, v81
	v_pk_fma_f32 v[62:63], v[88:89], v[62:63], s[94:95] op_sel_hi:[1,1,0]
	v_pk_mul_f32 v[86:87], v[78:79], v[60:61]
	v_pk_fma_f32 v[60:61], v[78:79], v[60:61], v[78:79] neg_lo:[1,0,0] neg_hi:[1,0,0]
	v_pk_fma_f32 v[62:63], v[88:89], v[62:63], s[84:85] op_sel_hi:[1,1,0]
	v_cndmask_b32_e32 v85, v94, v92, vcc
	v_cmp_gt_f32_e32 vcc, 0, v78
	v_pk_mul_f32 v[62:63], v[88:89], v[62:63]
	v_pk_mul_f32 v[90:91], v[76:77], v[64:65]
	v_cndmask_b32_e32 v84, v60, v86, vcc
	v_cmp_gt_f32_e32 vcc, 0, v75
	v_pk_mul_f32 v[62:63], v[80:81], v[62:63]
	v_pk_fma_f32 v[64:65], v[76:77], v[64:65], v[76:77] neg_lo:[1,0,0] neg_hi:[1,0,0]
	v_cndmask_b32_e32 v83, v95, v93, vcc
	v_cmp_gt_f32_e32 vcc, 0, v79
	v_pk_mul_f32 v[96:97], v[66:67], v[62:63]
	v_pk_fma_f32 v[62:63], v[66:67], v[62:63], v[66:67] neg_lo:[1,0,0] neg_hi:[1,0,0]
	v_cndmask_b32_e32 v82, v61, v87, vcc
	v_cmp_gt_f32_e32 vcc, 0, v66
	v_pk_add_f32 v[60:61], v[84:85], v[82:83]
	s_and_b64 s[14:15], s[12:13], exec
	v_cndmask_b32_e32 v89, v62, v96, vcc
	v_cmp_gt_f32_e32 vcc, 0, v76
	s_cselect_b32 s15, s64, s76
	s_cselect_b32 s14, s63, s65
	v_cndmask_b32_e32 v88, v64, v90, vcc
	v_cmp_gt_f32_e32 vcc, 0, v67
	v_lshl_add_u64 v[80:81], s[14:15], 0, v[70:71]
	v_mov_b32_e32 v124, v2
	v_cndmask_b32_e32 v87, v63, v97, vcc
	v_cmp_gt_f32_e32 vcc, 0, v77
	v_lshl_add_u64 v[80:81], v[124:125], 1, v[80:81]
	s_mov_b64 s[14:15], 0
	v_cndmask_b32_e32 v86, v65, v91, vcc
	v_pk_add_f32 v[62:63], v[88:89], v[86:87]
	v_pk_mul_f32 v[64:65], v[86:87], v[86:87]
	v_pk_add_f32 v[62:63], v[60:61], v[62:63]
	v_pk_mul_f32 v[60:61], v[82:83], v[82:83]
	v_pk_fma_f32 v[64:65], v[88:89], v[88:89], v[64:65]
	v_pk_fma_f32 v[60:61], v[84:85], v[84:85], v[60:61]
	v_add_f32_e32 v62, v62, v63
	v_pk_add_f32 v[60:61], v[60:61], v[64:65]
	s_nop 0
	v_add_f32_e32 v60, v60, v61

.LBB0_135:
	s_nop 0
	v_add_u32_e32 v52, 0x90, v142
	s_waitcnt lgkmcnt(0)
	v_mad_i64_i32 v[54:55], s[14:15], v52, s95, 0
	s_and_b64 vcc, exec, s[44:45]
	s_mov_b64 s[14:15], -1
	v_fmamk_f32 v53, v213, 0x3a800000, v195
	v_rsq_f32_e32 v56, v53
	s_nop 0
	v_pk_mul_f32 v[60:61], v[50:51], v[56:57] op_sel_hi:[1,0]
	v_pk_mul_f32 v[62:63], v[48:49], v[56:57] op_sel_hi:[1,0]
	v_pk_mul_f32 v[50:51], v[46:47], v[56:57] op_sel_hi:[1,0]
	v_pk_mul_f32 v[58:59], v[44:45], v[56:57] op_sel_hi:[1,0]
	s_cbranch_vccnz .LBB0_137
	v_and_b32_e32 v45, 0x7fffffff, v63
	v_and_b32_e32 v44, 0x7fffffff, v62
	v_pk_fma_f32 v[44:45], v[44:45], s[52:53], 1.0 op_sel_hi:[1,0,0]
	v_mov_b64_e32 v[46:47], s[24:25]
	v_rcp_f32_e32 v44, v44
	v_rcp_f32_e32 v45, v45
	v_pk_mul_f32 v[64:65], v[62:63], v[62:63]
	v_and_b32_e32 v67, 0x7fffffff, v61
	v_and_b32_e32 v66, 0x7fffffff, v60
	v_pk_fma_f32 v[48:49], v[44:45], s[62:63], v[46:47] op_sel_hi:[1,0,0]
	v_pk_mul_f32 v[64:65], v[64:65], s[86:87] op_sel_hi:[1,0]
	v_pk_fma_f32 v[66:67], v[66:67], s[52:53], 1.0 op_sel_hi:[1,0,0]
	v_pk_fma_f32 v[48:49], v[44:45], v[48:49], s[30:31] op_sel_hi:[1,1,0]
	v_exp_f32_e32 v64, v64
	v_exp_f32_e32 v65, v65
	v_rcp_f32_e32 v66, v66
	v_rcp_f32_e32 v67, v67
	v_pk_fma_f32 v[48:49], v[44:45], v[48:49], s[94:95] op_sel_hi:[1,1,0]
	v_pk_mul_f32 v[68:69], v[58:59], v[58:59]
	v_pk_fma_f32 v[48:49], v[44:45], v[48:49], s[84:85] op_sel_hi:[1,1,0]
	v_pk_mul_f32 v[68:69], v[68:69], s[86:87] op_sel_hi:[1,0]
	v_pk_mul_f32 v[44:45], v[44:45], v[48:49]
	v_pk_mul_f32 v[48:49], v[60:61], v[60:61]
	v_pk_mul_f32 v[44:45], v[64:65], v[44:45]
	v_pk_fma_f32 v[64:65], v[66:67], s[62:63], v[46:47] op_sel_hi:[1,0,0]
	v_pk_mul_f32 v[48:49], v[48:49], s[86:87] op_sel_hi:[1,0]
	v_pk_fma_f32 v[64:65], v[66:67], v[64:65], s[30:31] op_sel_hi:[1,1,0]
	v_exp_f32_e32 v48, v48
	v_pk_fma_f32 v[64:65], v[66:67], v[64:65], s[94:95] op_sel_hi:[1,1,0]
	v_exp_f32_e32 v49, v49
	v_pk_fma_f32 v[64:65], v[66:67], v[64:65], s[84:85] op_sel_hi:[1,1,0]
	v_and_b32_e32 v73, 0x7fffffff, v51
	v_pk_mul_f32 v[64:65], v[66:67], v[64:65]
	v_and_b32_e32 v67, 0x7fffffff, v59
	v_and_b32_e32 v66, 0x7fffffff, v58
	v_pk_fma_f32 v[66:67], v[66:67], s[52:53], 1.0 op_sel_hi:[1,0,0]
	v_pk_mul_f32 v[48:49], v[48:49], v[64:65]
	v_rcp_f32_e32 v66, v66
	v_rcp_f32_e32 v67, v67
	v_and_b32_e32 v72, 0x7fffffff, v50
	v_exp_f32_e32 v68, v68
	v_exp_f32_e32 v69, v69
	v_pk_fma_f32 v[64:65], v[66:67], s[62:63], v[46:47] op_sel_hi:[1,0,0]
	v_pk_fma_f32 v[72:73], v[72:73], s[52:53], 1.0 op_sel_hi:[1,0,0]
	v_pk_fma_f32 v[64:65], v[66:67], v[64:65], s[30:31] op_sel_hi:[1,1,0]
	v_rcp_f32_e32 v72, v72
	v_pk_fma_f32 v[64:65], v[66:67], v[64:65], s[94:95] op_sel_hi:[1,1,0]
	v_rcp_f32_e32 v73, v73
	v_pk_fma_f32 v[64:65], v[66:67], v[64:65], s[84:85] op_sel_hi:[1,1,0]
	v_cmp_gt_f32_e32 vcc, 0, v58
	v_pk_mul_f32 v[64:65], v[66:67], v[64:65]
	v_pk_mul_f32 v[66:67], v[50:51], v[50:51]
	v_pk_mul_f32 v[64:65], v[68:69], v[64:65]
	v_pk_fma_f32 v[46:47], v[72:73], s[62:63], v[46:47] op_sel_hi:[1,0,0]
	v_pk_mul_f32 v[76:77], v[58:59], v[64:65]
	v_pk_fma_f32 v[78:79], v[58:59], v[64:65], v[58:59] neg_lo:[1,0,0] neg_hi:[1,0,0]
	v_pk_mul_f32 v[64:65], v[66:67], s[86:87] op_sel_hi:[1,0]
	v_pk_fma_f32 v[46:47], v[72:73], v[46:47], s[30:31] op_sel_hi:[1,1,0]
	v_exp_f32_e32 v64, v64
	v_exp_f32_e32 v65, v65
	v_pk_fma_f32 v[46:47], v[72:73], v[46:47], s[94:95] op_sel_hi:[1,1,0]
	v_pk_mul_f32 v[70:71], v[62:63], v[44:45]
	v_pk_fma_f32 v[44:45], v[62:63], v[44:45], v[62:63] neg_lo:[1,0,0] neg_hi:[1,0,0]
	v_pk_fma_f32 v[46:47], v[72:73], v[46:47], s[84:85] op_sel_hi:[1,1,0]
	v_cndmask_b32_e32 v69, v78, v76, vcc
	v_cmp_gt_f32_e32 vcc, 0, v62
	v_pk_mul_f32 v[46:47], v[72:73], v[46:47]
	v_pk_mul_f32 v[74:75], v[60:61], v[48:49]
	v_cndmask_b32_e32 v68, v44, v70, vcc
	v_cmp_gt_f32_e32 vcc, 0, v59
	v_pk_mul_f32 v[46:47], v[64:65], v[46:47]
	v_pk_fma_f32 v[48:49], v[60:61], v[48:49], v[60:61] neg_lo:[1,0,0] neg_hi:[1,0,0]
	v_cndmask_b32_e32 v67, v79, v77, vcc
	v_cmp_gt_f32_e32 vcc, 0, v63
	v_pk_mul_f32 v[80:81], v[50:51], v[46:47]
	v_pk_fma_f32 v[46:47], v[50:51], v[46:47], v[50:51] neg_lo:[1,0,0] neg_hi:[1,0,0]
	v_cndmask_b32_e32 v66, v45, v71, vcc
	v_cmp_gt_f32_e32 vcc, 0, v50
	v_pk_add_f32 v[44:45], v[68:69], v[66:67]
	s_and_b64 s[14:15], s[12:13], exec
	v_cndmask_b32_e32 v73, v46, v80, vcc
	v_cmp_gt_f32_e32 vcc, 0, v60
	s_cselect_b32 s15, s64, s76
	s_cselect_b32 s14, s63, s65
	v_cndmask_b32_e32 v72, v48, v74, vcc
	v_cmp_gt_f32_e32 vcc, 0, v51
	v_lshl_add_u64 v[64:65], s[14:15], 0, v[54:55]
	v_mov_b32_e32 v124, v2
	v_cndmask_b32_e32 v71, v47, v81, vcc
	v_cmp_gt_f32_e32 vcc, 0, v61
	v_lshl_add_u64 v[64:65], v[124:125], 1, v[64:65]
	s_mov_b64 s[14:15], 0
	v_cndmask_b32_e32 v70, v49, v75, vcc
	v_pk_add_f32 v[46:47], v[72:73], v[70:71]
	v_pk_mul_f32 v[48:49], v[70:71], v[70:71]
	v_pk_add_f32 v[46:47], v[44:45], v[46:47]
	v_pk_mul_f32 v[44:45], v[66:67], v[66:67]
	v_pk_fma_f32 v[48:49], v[72:73], v[72:73], v[48:49]
	v_pk_fma_f32 v[44:45], v[68:69], v[68:69], v[44:45]
	v_add_f32_e32 v46, v46, v47
	v_pk_add_f32 v[44:45], v[44:45], v[48:49]
	s_nop 0
	v_add_f32_e32 v44, v44, v45

.LBB0_147:
	s_nop 0
	v_add_u32_e32 v36, 0xa0, v142
	s_waitcnt lgkmcnt(0)
	v_mad_i64_i32 v[38:39], s[14:15], v36, s95, 0
	s_and_b64 vcc, exec, s[44:45]
	s_mov_b64 s[14:15], -1
	v_fmamk_f32 v37, v214, 0x3a800000, v195
	v_rsq_f32_e32 v40, v37
	s_nop 0
	v_pk_mul_f32 v[44:45], v[34:35], v[40:41] op_sel_hi:[1,0]
	v_pk_mul_f32 v[46:47], v[32:33], v[40:41] op_sel_hi:[1,0]
	v_pk_mul_f32 v[34:35], v[30:31], v[40:41] op_sel_hi:[1,0]
	v_pk_mul_f32 v[42:43], v[28:29], v[40:41] op_sel_hi:[1,0]
	s_cbranch_vccnz .LBB0_149
	v_and_b32_e32 v29, 0x7fffffff, v47
	v_and_b32_e32 v28, 0x7fffffff, v46
	v_pk_fma_f32 v[28:29], v[28:29], s[52:53], 1.0 op_sel_hi:[1,0,0]
	v_mov_b64_e32 v[30:31], s[24:25]
	v_rcp_f32_e32 v28, v28
	v_rcp_f32_e32 v29, v29
	v_pk_mul_f32 v[48:49], v[46:47], v[46:47]
	v_and_b32_e32 v51, 0x7fffffff, v45
	v_and_b32_e32 v50, 0x7fffffff, v44
	v_pk_fma_f32 v[32:33], v[28:29], s[62:63], v[30:31] op_sel_hi:[1,0,0]
	v_pk_mul_f32 v[48:49], v[48:49], s[86:87] op_sel_hi:[1,0]
	v_pk_fma_f32 v[50:51], v[50:51], s[52:53], 1.0 op_sel_hi:[1,0,0]
	v_pk_fma_f32 v[32:33], v[28:29], v[32:33], s[30:31] op_sel_hi:[1,1,0]
	v_exp_f32_e32 v48, v48
	v_exp_f32_e32 v49, v49
	v_rcp_f32_e32 v50, v50
	v_rcp_f32_e32 v51, v51
	v_pk_fma_f32 v[32:33], v[28:29], v[32:33], s[94:95] op_sel_hi:[1,1,0]
	v_pk_mul_f32 v[52:53], v[42:43], v[42:43]
	v_pk_fma_f32 v[32:33], v[28:29], v[32:33], s[84:85] op_sel_hi:[1,1,0]
	v_pk_mul_f32 v[52:53], v[52:53], s[86:87] op_sel_hi:[1,0]
	v_pk_mul_f32 v[28:29], v[28:29], v[32:33]
	v_pk_mul_f32 v[32:33], v[44:45], v[44:45]
	v_pk_mul_f32 v[28:29], v[48:49], v[28:29]
	v_pk_fma_f32 v[48:49], v[50:51], s[62:63], v[30:31] op_sel_hi:[1,0,0]
	v_pk_mul_f32 v[32:33], v[32:33], s[86:87] op_sel_hi:[1,0]
	v_pk_fma_f32 v[48:49], v[50:51], v[48:49], s[30:31] op_sel_hi:[1,1,0]
	v_exp_f32_e32 v32, v32
	v_pk_fma_f32 v[48:49], v[50:51], v[48:49], s[94:95] op_sel_hi:[1,1,0]
	v_exp_f32_e32 v33, v33
	v_pk_fma_f32 v[48:49], v[50:51], v[48:49], s[84:85] op_sel_hi:[1,1,0]
	v_and_b32_e32 v57, 0x7fffffff, v35
	v_pk_mul_f32 v[48:49], v[50:51], v[48:49]
	v_and_b32_e32 v51, 0x7fffffff, v43
	v_and_b32_e32 v50, 0x7fffffff, v42
	v_pk_fma_f32 v[50:51], v[50:51], s[52:53], 1.0 op_sel_hi:[1,0,0]
	v_pk_mul_f32 v[32:33], v[32:33], v[48:49]
	v_rcp_f32_e32 v50, v50
	v_rcp_f32_e32 v51, v51
	v_and_b32_e32 v56, 0x7fffffff, v34
	v_exp_f32_e32 v52, v52
	v_exp_f32_e32 v53, v53
	v_pk_fma_f32 v[48:49], v[50:51], s[62:63], v[30:31] op_sel_hi:[1,0,0]
	v_pk_fma_f32 v[56:57], v[56:57], s[52:53], 1.0 op_sel_hi:[1,0,0]
	v_pk_fma_f32 v[48:49], v[50:51], v[48:49], s[30:31] op_sel_hi:[1,1,0]
	v_rcp_f32_e32 v56, v56
	v_pk_fma_f32 v[48:49], v[50:51], v[48:49], s[94:95] op_sel_hi:[1,1,0]
	v_rcp_f32_e32 v57, v57
	v_pk_fma_f32 v[48:49], v[50:51], v[48:49], s[84:85] op_sel_hi:[1,1,0]
	v_cmp_gt_f32_e32 vcc, 0, v42
	v_pk_mul_f32 v[48:49], v[50:51], v[48:49]
	v_pk_mul_f32 v[50:51], v[34:35], v[34:35]
	v_pk_mul_f32 v[48:49], v[52:53], v[48:49]
	v_pk_fma_f32 v[30:31], v[56:57], s[62:63], v[30:31] op_sel_hi:[1,0,0]
	v_pk_mul_f32 v[60:61], v[42:43], v[48:49]
	v_pk_fma_f32 v[62:63], v[42:43], v[48:49], v[42:43] neg_lo:[1,0,0] neg_hi:[1,0,0]
	v_pk_mul_f32 v[48:49], v[50:51], s[86:87] op_sel_hi:[1,0]
	v_pk_fma_f32 v[30:31], v[56:57], v[30:31], s[30:31] op_sel_hi:[1,1,0]
	v_exp_f32_e32 v48, v48
	v_exp_f32_e32 v49, v49
	v_pk_fma_f32 v[30:31], v[56:57], v[30:31], s[94:95] op_sel_hi:[1,1,0]
	v_pk_mul_f32 v[54:55], v[46:47], v[28:29]
	v_pk_fma_f32 v[28:29], v[46:47], v[28:29], v[46:47] neg_lo:[1,0,0] neg_hi:[1,0,0]
	v_pk_fma_f32 v[30:31], v[56:57], v[30:31], s[84:85] op_sel_hi:[1,1,0]
	v_cndmask_b32_e32 v53, v62, v60, vcc
	v_cmp_gt_f32_e32 vcc, 0, v46
	v_pk_mul_f32 v[30:31], v[56:57], v[30:31]
	v_pk_mul_f32 v[58:59], v[44:45], v[32:33]
	v_cndmask_b32_e32 v52, v28, v54, vcc
	v_cmp_gt_f32_e32 vcc, 0, v43
	v_pk_mul_f32 v[30:31], v[48:49], v[30:31]
	v_pk_fma_f32 v[32:33], v[44:45], v[32:33], v[44:45] neg_lo:[1,0,0] neg_hi:[1,0,0]
	v_cndmask_b32_e32 v51, v63, v61, vcc
	v_cmp_gt_f32_e32 vcc, 0, v47
	v_pk_mul_f32 v[64:65], v[34:35], v[30:31]
	v_pk_fma_f32 v[30:31], v[34:35], v[30:31], v[34:35] neg_lo:[1,0,0] neg_hi:[1,0,0]
	v_cndmask_b32_e32 v50, v29, v55, vcc
	v_cmp_gt_f32_e32 vcc, 0, v34
	v_pk_add_f32 v[28:29], v[52:53], v[50:51]
	s_and_b64 s[14:15], s[12:13], exec
	v_cndmask_b32_e32 v57, v30, v64, vcc
	v_cmp_gt_f32_e32 vcc, 0, v44
	s_cselect_b32 s15, s64, s76
	s_cselect_b32 s14, s63, s65
	v_cndmask_b32_e32 v56, v32, v58, vcc
	v_cmp_gt_f32_e32 vcc, 0, v35
	v_lshl_add_u64 v[48:49], s[14:15], 0, v[38:39]
	v_mov_b32_e32 v124, v2
	v_cndmask_b32_e32 v55, v31, v65, vcc
	v_cmp_gt_f32_e32 vcc, 0, v45
	v_lshl_add_u64 v[48:49], v[124:125], 1, v[48:49]
	s_mov_b64 s[14:15], 0
	v_cndmask_b32_e32 v54, v33, v59, vcc
	v_pk_add_f32 v[30:31], v[56:57], v[54:55]
	v_pk_mul_f32 v[32:33], v[54:55], v[54:55]
	v_pk_add_f32 v[30:31], v[28:29], v[30:31]
	v_pk_mul_f32 v[28:29], v[50:51], v[50:51]
	v_pk_fma_f32 v[32:33], v[56:57], v[56:57], v[32:33]
	v_pk_fma_f32 v[28:29], v[52:53], v[52:53], v[28:29]
	v_add_f32_e32 v30, v30, v31
	v_pk_add_f32 v[28:29], v[28:29], v[32:33]
	s_nop 0
	v_add_f32_e32 v28, v28, v29

.LBB0_159:
	s_nop 0
	v_add_u32_e32 v20, 0xb0, v142
	s_waitcnt lgkmcnt(0)
	v_mad_i64_i32 v[22:23], s[14:15], v20, s95, 0
	s_and_b64 vcc, exec, s[44:45]
	s_mov_b64 s[14:15], -1
	v_fmamk_f32 v21, v215, 0x3a800000, v195
	v_rsq_f32_e32 v24, v21
	s_nop 0
	v_pk_mul_f32 v[28:29], v[18:19], v[24:25] op_sel_hi:[1,0]
	v_pk_mul_f32 v[30:31], v[16:17], v[24:25] op_sel_hi:[1,0]
	v_pk_mul_f32 v[18:19], v[14:15], v[24:25] op_sel_hi:[1,0]
	v_pk_mul_f32 v[26:27], v[12:13], v[24:25] op_sel_hi:[1,0]
	s_cbranch_vccnz .LBB0_161
	v_and_b32_e32 v13, 0x7fffffff, v31
	v_and_b32_e32 v12, 0x7fffffff, v30
	v_pk_fma_f32 v[12:13], v[12:13], s[52:53], 1.0 op_sel_hi:[1,0,0]
	v_mov_b64_e32 v[14:15], s[24:25]
	v_rcp_f32_e32 v12, v12
	v_rcp_f32_e32 v13, v13
	v_pk_mul_f32 v[32:33], v[30:31], v[30:31]
	v_and_b32_e32 v35, 0x7fffffff, v29
	v_and_b32_e32 v34, 0x7fffffff, v28
	v_pk_fma_f32 v[16:17], v[12:13], s[62:63], v[14:15] op_sel_hi:[1,0,0]
	v_pk_mul_f32 v[32:33], v[32:33], s[86:87] op_sel_hi:[1,0]
	v_pk_fma_f32 v[34:35], v[34:35], s[52:53], 1.0 op_sel_hi:[1,0,0]
	v_pk_fma_f32 v[16:17], v[12:13], v[16:17], s[30:31] op_sel_hi:[1,1,0]
	v_exp_f32_e32 v32, v32
	v_exp_f32_e32 v33, v33
	v_rcp_f32_e32 v34, v34
	v_rcp_f32_e32 v35, v35
	v_pk_fma_f32 v[16:17], v[12:13], v[16:17], s[94:95] op_sel_hi:[1,1,0]
	v_pk_mul_f32 v[36:37], v[26:27], v[26:27]
	v_pk_fma_f32 v[16:17], v[12:13], v[16:17], s[84:85] op_sel_hi:[1,1,0]
	v_pk_mul_f32 v[36:37], v[36:37], s[86:87] op_sel_hi:[1,0]
	v_pk_mul_f32 v[12:13], v[12:13], v[16:17]
	v_pk_mul_f32 v[16:17], v[28:29], v[28:29]
	v_pk_mul_f32 v[12:13], v[32:33], v[12:13]
	v_pk_fma_f32 v[32:33], v[34:35], s[62:63], v[14:15] op_sel_hi:[1,0,0]
	v_pk_mul_f32 v[16:17], v[16:17], s[86:87] op_sel_hi:[1,0]
	v_pk_fma_f32 v[32:33], v[34:35], v[32:33], s[30:31] op_sel_hi:[1,1,0]
	v_exp_f32_e32 v16, v16
	v_pk_fma_f32 v[32:33], v[34:35], v[32:33], s[94:95] op_sel_hi:[1,1,0]
	v_exp_f32_e32 v17, v17
	v_pk_fma_f32 v[32:33], v[34:35], v[32:33], s[84:85] op_sel_hi:[1,1,0]
	v_and_b32_e32 v41, 0x7fffffff, v19
	v_pk_mul_f32 v[32:33], v[34:35], v[32:33]
	v_and_b32_e32 v35, 0x7fffffff, v27
	v_and_b32_e32 v34, 0x7fffffff, v26
	v_pk_fma_f32 v[34:35], v[34:35], s[52:53], 1.0 op_sel_hi:[1,0,0]
	v_pk_mul_f32 v[16:17], v[16:17], v[32:33]
	v_rcp_f32_e32 v34, v34
	v_rcp_f32_e32 v35, v35
	v_and_b32_e32 v40, 0x7fffffff, v18
	v_exp_f32_e32 v36, v36
	v_exp_f32_e32 v37, v37
	v_pk_fma_f32 v[32:33], v[34:35], s[62:63], v[14:15] op_sel_hi:[1,0,0]
	v_pk_fma_f32 v[40:41], v[40:41], s[52:53], 1.0 op_sel_hi:[1,0,0]
	v_pk_fma_f32 v[32:33], v[34:35], v[32:33], s[30:31] op_sel_hi:[1,1,0]
	v_rcp_f32_e32 v40, v40
	v_pk_fma_f32 v[32:33], v[34:35], v[32:33], s[94:95] op_sel_hi:[1,1,0]
	v_rcp_f32_e32 v41, v41
	v_pk_fma_f32 v[32:33], v[34:35], v[32:33], s[84:85] op_sel_hi:[1,1,0]
	v_cmp_gt_f32_e32 vcc, 0, v26
	v_pk_mul_f32 v[32:33], v[34:35], v[32:33]
	v_pk_mul_f32 v[34:35], v[18:19], v[18:19]
	v_pk_mul_f32 v[32:33], v[36:37], v[32:33]
	v_pk_fma_f32 v[14:15], v[40:41], s[62:63], v[14:15] op_sel_hi:[1,0,0]
	v_pk_mul_f32 v[44:45], v[26:27], v[32:33]
	v_pk_fma_f32 v[46:47], v[26:27], v[32:33], v[26:27] neg_lo:[1,0,0] neg_hi:[1,0,0]
	v_pk_mul_f32 v[32:33], v[34:35], s[86:87] op_sel_hi:[1,0]
	v_pk_fma_f32 v[14:15], v[40:41], v[14:15], s[30:31] op_sel_hi:[1,1,0]
	v_exp_f32_e32 v32, v32
	v_exp_f32_e32 v33, v33
	v_pk_fma_f32 v[14:15], v[40:41], v[14:15], s[94:95] op_sel_hi:[1,1,0]
	v_pk_mul_f32 v[38:39], v[30:31], v[12:13]
	v_pk_fma_f32 v[12:13], v[30:31], v[12:13], v[30:31] neg_lo:[1,0,0] neg_hi:[1,0,0]
	v_pk_fma_f32 v[14:15], v[40:41], v[14:15], s[84:85] op_sel_hi:[1,1,0]
	v_cndmask_b32_e32 v37, v46, v44, vcc
	v_cmp_gt_f32_e32 vcc, 0, v30
	v_pk_mul_f32 v[14:15], v[40:41], v[14:15]
	v_pk_mul_f32 v[42:43], v[28:29], v[16:17]
	v_cndmask_b32_e32 v36, v12, v38, vcc
	v_cmp_gt_f32_e32 vcc, 0, v27
	v_pk_mul_f32 v[14:15], v[32:33], v[14:15]
	v_pk_fma_f32 v[16:17], v[28:29], v[16:17], v[28:29] neg_lo:[1,0,0] neg_hi:[1,0,0]
	v_cndmask_b32_e32 v35, v47, v45, vcc
	v_cmp_gt_f32_e32 vcc, 0, v31
	v_pk_mul_f32 v[48:49], v[18:19], v[14:15]
	v_pk_fma_f32 v[14:15], v[18:19], v[14:15], v[18:19] neg_lo:[1,0,0] neg_hi:[1,0,0]
	v_cndmask_b32_e32 v34, v13, v39, vcc
	v_cmp_gt_f32_e32 vcc, 0, v18
	v_pk_add_f32 v[12:13], v[36:37], v[34:35]
	s_and_b64 s[14:15], s[12:13], exec
	v_cndmask_b32_e32 v41, v14, v48, vcc
	v_cmp_gt_f32_e32 vcc, 0, v28
	s_cselect_b32 s15, s64, s76
	s_cselect_b32 s14, s63, s65
	v_cndmask_b32_e32 v40, v16, v42, vcc
	v_cmp_gt_f32_e32 vcc, 0, v19
	v_lshl_add_u64 v[32:33], s[14:15], 0, v[22:23]
	v_mov_b32_e32 v124, v2
	v_cndmask_b32_e32 v39, v15, v49, vcc
	v_cmp_gt_f32_e32 vcc, 0, v29
	v_lshl_add_u64 v[32:33], v[124:125], 1, v[32:33]
	s_mov_b64 s[14:15], 0
	v_cndmask_b32_e32 v38, v17, v43, vcc
	v_pk_add_f32 v[14:15], v[40:41], v[38:39]
	v_pk_mul_f32 v[16:17], v[38:39], v[38:39]
	v_pk_add_f32 v[14:15], v[12:13], v[14:15]
	v_pk_mul_f32 v[12:13], v[34:35], v[34:35]
	v_pk_fma_f32 v[16:17], v[40:41], v[40:41], v[16:17]
	v_pk_fma_f32 v[12:13], v[36:37], v[36:37], v[12:13]
	v_add_f32_e32 v14, v14, v15
	v_pk_add_f32 v[12:13], v[12:13], v[16:17]
	s_nop 0
	v_add_f32_e32 v12, v12, v13

.LBB0_218:
	v_lshl_add_u32 v182, s17, 8, v199
	v_ashrrev_i32_e32 v183, 31, v182
	v_lshl_add_u64 v[184:185], v[182:183], 2, s[28:29]
	global_load_dword v208, v[184:185], off
	global_load_dword v209, v[184:185], off offset:64
	global_load_dword v210, v[184:185], off offset:128
	global_load_dword v211, v[184:185], off offset:192
	global_load_dword v212, v[184:185], off offset:512
	global_load_dword v213, v[184:185], off offset:576
	global_load_dword v214, v[184:185], off offset:640
	global_load_dword v215, v[184:185], off offset:704
	s_add_i32 s0, s16, 2
	s_cmp_gt_u32 s0, 4
	v_mad_i64_i32 v[186:187], s[0:1], v182, s95, 0
	s_cselect_b64 s[42:43], -1, 0
	s_add_i32 s0, s16, -6
	s_cmp_gt_u32 s0, 2
	s_mov_b64 s[44:45], -1
	v_lshlrev_b64 v[188:189], 9, v[182:183]
	s_cselect_b64 s[0:1], -1, 0
	s_and_b64 vcc, exec, s[14:15]
	s_waitcnt vmcnt(0)
	v_fmamk_f32 v148, v208, 0x3a800000, v195
	v_rsq_f32_e32 v190, v148
	s_nop 0
	v_pk_mul_f32 v[146:147], v[146:147], v[190:191] op_sel_hi:[1,0]
	v_pk_mul_f32 v[144:145], v[144:145], v[190:191] op_sel_hi:[1,0]
	v_pk_mul_f32 v[142:143], v[142:143], v[190:191] op_sel_hi:[1,0]
	v_pk_mul_f32 v[140:141], v[140:141], v[190:191] op_sel_hi:[1,0]
	s_cbranch_vccz .LBB0_232
	s_and_b64 vcc, exec, s[42:43]
	s_cbranch_vccz .LBB0_229
	s_and_b64 vcc, exec, s[0:1]
	s_cbranch_vccz .LBB0_226
	s_and_b64 vcc, exec, s[12:13]
	s_cbranch_vccz .LBB0_223
	v_lshl_add_u64 v[148:149], s[64:65], 0, v[188:189]
	v_ashrrev_i32_e32 v151, 31, v2
	v_mov_b32_e32 v150, v2
	v_lshl_add_u64 v[192:193], v[150:151], 1, v[148:149]
	v_pk_mul_f32 v[150:151], v[146:147], s[88:89] op_sel_hi:[1,0]
	v_pk_mul_f32 v[148:149], v[144:145], s[88:89] op_sel_hi:[1,0]
	v_pk_mul_f32 v[154:155], v[142:143], s[88:89] op_sel_hi:[1,0]
	v_pk_mul_f32 v[152:153], v[140:141], s[88:89] op_sel_hi:[1,0]
	s_mov_b64 s[44:45], 0

.LBB0_250:
	s_nop 0
	v_or_b32_e32 v146, 16, v182
	v_ashrrev_i32_e32 v147, 31, v146
	v_mad_i64_i32 v[140:141], s[14:15], v146, s95, 0
	s_and_b64 vcc, exec, s[44:45]
	v_lshlrev_b64 v[142:143], 9, v[146:147]
	s_mov_b64 s[14:15], -1
	v_fmamk_f32 v132, v209, 0x3a800000, v195
	v_rsq_f32_e32 v144, v132
	s_nop 0
	v_pk_mul_f32 v[130:131], v[130:131], v[144:145] op_sel_hi:[1,0]
	v_pk_mul_f32 v[128:129], v[128:129], v[144:145] op_sel_hi:[1,0]
	v_pk_mul_f32 v[126:127], v[126:127], v[144:145] op_sel_hi:[1,0]
	v_pk_mul_f32 v[124:125], v[124:125], v[144:145] op_sel_hi:[1,0]
	s_cbranch_vccnz .LBB0_264
	s_and_b64 vcc, exec, s[42:43]
	s_cbranch_vccnz .LBB0_261
	s_andn2_b64 vcc, exec, s[0:1]
	s_cbranch_vccnz .LBB0_258
	s_andn2_b64 vcc, exec, s[12:13]
	s_cbranch_vccnz .LBB0_255
	v_lshl_add_u64 v[132:133], s[64:65], 0, v[142:143]
	v_ashrrev_i32_e32 v135, 31, v2
	v_mov_b32_e32 v134, v2
	v_lshl_add_u64 v[148:149], v[134:135], 1, v[132:133]
	v_pk_mul_f32 v[134:135], v[130:131], s[88:89] op_sel_hi:[1,0]
	v_pk_mul_f32 v[132:133], v[128:129], s[88:89] op_sel_hi:[1,0]
	v_pk_mul_f32 v[138:139], v[126:127], s[88:89] op_sel_hi:[1,0]
	v_pk_mul_f32 v[136:137], v[124:125], s[88:89] op_sel_hi:[1,0]
	s_mov_b64 s[14:15], 0

.LBB0_282:
	s_nop 0
	v_or_b32_e32 v130, 32, v182
	v_ashrrev_i32_e32 v131, 31, v130
	v_mad_i64_i32 v[124:125], s[14:15], v130, s95, 0
	s_and_b64 vcc, exec, s[44:45]
	v_lshlrev_b64 v[126:127], 9, v[130:131]
	s_mov_b64 s[14:15], -1
	v_fmamk_f32 v116, v210, 0x3a800000, v195
	v_rsq_f32_e32 v128, v116
	s_nop 0
	v_pk_mul_f32 v[114:115], v[114:115], v[128:129] op_sel_hi:[1,0]
	v_pk_mul_f32 v[112:113], v[112:113], v[128:129] op_sel_hi:[1,0]
	v_pk_mul_f32 v[110:111], v[110:111], v[128:129] op_sel_hi:[1,0]
	v_pk_mul_f32 v[108:109], v[108:109], v[128:129] op_sel_hi:[1,0]
	s_cbranch_vccnz .LBB0_296
	s_and_b64 vcc, exec, s[42:43]
	s_cbranch_vccnz .LBB0_293
	s_andn2_b64 vcc, exec, s[0:1]
	s_cbranch_vccnz .LBB0_290
	s_andn2_b64 vcc, exec, s[12:13]
	s_cbranch_vccnz .LBB0_287
	v_lshl_add_u64 v[116:117], s[64:65], 0, v[126:127]
	v_ashrrev_i32_e32 v119, 31, v2
	v_mov_b32_e32 v118, v2
	v_lshl_add_u64 v[132:133], v[118:119], 1, v[116:117]
	v_pk_mul_f32 v[118:119], v[114:115], s[88:89] op_sel_hi:[1,0]
	v_pk_mul_f32 v[116:117], v[112:113], s[88:89] op_sel_hi:[1,0]
	v_pk_mul_f32 v[122:123], v[110:111], s[88:89] op_sel_hi:[1,0]
	v_pk_mul_f32 v[120:121], v[108:109], s[88:89] op_sel_hi:[1,0]
	s_mov_b64 s[14:15], 0

.LBB0_314:
	s_nop 0
	v_or_b32_e32 v114, 48, v182
	v_ashrrev_i32_e32 v115, 31, v114
	v_mad_i64_i32 v[108:109], s[14:15], v114, s95, 0
	s_and_b64 vcc, exec, s[44:45]
	v_lshlrev_b64 v[110:111], 9, v[114:115]
	s_mov_b64 s[14:15], -1
	v_fmamk_f32 v100, v211, 0x3a800000, v195
	v_rsq_f32_e32 v112, v100
	s_nop 0
	v_pk_mul_f32 v[98:99], v[98:99], v[112:113] op_sel_hi:[1,0]
	v_pk_mul_f32 v[96:97], v[96:97], v[112:113] op_sel_hi:[1,0]
	v_pk_mul_f32 v[94:95], v[94:95], v[112:113] op_sel_hi:[1,0]
	v_pk_mul_f32 v[92:93], v[92:93], v[112:113] op_sel_hi:[1,0]
	s_cbranch_vccnz .LBB0_328
	s_and_b64 vcc, exec, s[42:43]
	s_cbranch_vccnz .LBB0_325
	s_andn2_b64 vcc, exec, s[0:1]
	s_cbranch_vccnz .LBB0_322
	s_andn2_b64 vcc, exec, s[12:13]
	s_cbranch_vccnz .LBB0_319
	v_lshl_add_u64 v[100:101], s[64:65], 0, v[110:111]
	v_ashrrev_i32_e32 v103, 31, v2
	v_mov_b32_e32 v102, v2
	v_lshl_add_u64 v[116:117], v[102:103], 1, v[100:101]
	v_pk_mul_f32 v[102:103], v[98:99], s[88:89] op_sel_hi:[1,0]
	v_pk_mul_f32 v[100:101], v[96:97], s[88:89] op_sel_hi:[1,0]
	v_pk_mul_f32 v[106:107], v[94:95], s[88:89] op_sel_hi:[1,0]
	v_pk_mul_f32 v[104:105], v[92:93], s[88:89] op_sel_hi:[1,0]
	s_mov_b64 s[14:15], 0

.LBB0_346:
	s_nop 0
	v_add_u32_e32 v98, 0x80, v182
	v_ashrrev_i32_e32 v99, 31, v98
	v_mad_i64_i32 v[92:93], s[14:15], v98, s95, 0
	s_and_b64 vcc, exec, s[44:45]
	v_lshlrev_b64 v[94:95], 9, v[98:99]
	s_mov_b64 s[14:15], -1
	v_fmamk_f32 v84, v212, 0x3a800000, v195
	v_rsq_f32_e32 v96, v84
	s_nop 0
	v_pk_mul_f32 v[82:83], v[82:83], v[96:97] op_sel_hi:[1,0]
	v_pk_mul_f32 v[80:81], v[80:81], v[96:97] op_sel_hi:[1,0]
	v_pk_mul_f32 v[78:79], v[78:79], v[96:97] op_sel_hi:[1,0]
	v_pk_mul_f32 v[76:77], v[76:77], v[96:97] op_sel_hi:[1,0]
	s_cbranch_vccnz .LBB0_360
	s_and_b64 vcc, exec, s[42:43]
	s_cbranch_vccnz .LBB0_357
	s_andn2_b64 vcc, exec, s[0:1]
	s_cbranch_vccnz .LBB0_354
	s_andn2_b64 vcc, exec, s[12:13]
	s_cbranch_vccnz .LBB0_351
	v_lshl_add_u64 v[84:85], s[64:65], 0, v[94:95]
	v_ashrrev_i32_e32 v87, 31, v2
	v_mov_b32_e32 v86, v2
	v_lshl_add_u64 v[100:101], v[86:87], 1, v[84:85]
	v_pk_mul_f32 v[86:87], v[82:83], s[88:89] op_sel_hi:[1,0]
	v_pk_mul_f32 v[84:85], v[80:81], s[88:89] op_sel_hi:[1,0]
	v_pk_mul_f32 v[90:91], v[78:79], s[88:89] op_sel_hi:[1,0]
	v_pk_mul_f32 v[88:89], v[76:77], s[88:89] op_sel_hi:[1,0]
	s_mov_b64 s[14:15], 0

.LBB0_378:
	s_nop 0
	v_add_u32_e32 v82, 0x90, v182
	v_ashrrev_i32_e32 v83, 31, v82
	v_mad_i64_i32 v[76:77], s[14:15], v82, s95, 0
	s_and_b64 vcc, exec, s[44:45]
	v_lshlrev_b64 v[78:79], 9, v[82:83]
	s_mov_b64 s[14:15], -1
	v_fmamk_f32 v68, v213, 0x3a800000, v195
	v_rsq_f32_e32 v80, v68
	s_nop 0
	v_pk_mul_f32 v[66:67], v[66:67], v[80:81] op_sel_hi:[1,0]
	v_pk_mul_f32 v[64:65], v[64:65], v[80:81] op_sel_hi:[1,0]
	v_pk_mul_f32 v[62:63], v[62:63], v[80:81] op_sel_hi:[1,0]
	v_pk_mul_f32 v[60:61], v[60:61], v[80:81] op_sel_hi:[1,0]
	s_cbranch_vccnz .LBB0_392
	s_and_b64 vcc, exec, s[42:43]
	s_cbranch_vccnz .LBB0_389
	s_andn2_b64 vcc, exec, s[0:1]
	s_cbranch_vccnz .LBB0_386
	s_andn2_b64 vcc, exec, s[12:13]
	s_cbranch_vccnz .LBB0_383
	v_lshl_add_u64 v[68:69], s[64:65], 0, v[78:79]
	v_ashrrev_i32_e32 v71, 31, v2
	v_mov_b32_e32 v70, v2
	v_lshl_add_u64 v[84:85], v[70:71], 1, v[68:69]
	v_pk_mul_f32 v[70:71], v[66:67], s[88:89] op_sel_hi:[1,0]
	v_pk_mul_f32 v[68:69], v[64:65], s[88:89] op_sel_hi:[1,0]
	v_pk_mul_f32 v[74:75], v[62:63], s[88:89] op_sel_hi:[1,0]
	v_pk_mul_f32 v[72:73], v[60:61], s[88:89] op_sel_hi:[1,0]
	s_mov_b64 s[14:15], 0

.LBB0_410:
	s_nop 0
	v_add_u32_e32 v66, 0xa0, v182
	v_ashrrev_i32_e32 v67, 31, v66
	v_mad_i64_i32 v[60:61], s[14:15], v66, s95, 0
	s_and_b64 vcc, exec, s[44:45]
	v_lshlrev_b64 v[62:63], 9, v[66:67]
	s_mov_b64 s[14:15], -1
	v_fmamk_f32 v52, v214, 0x3a800000, v195
	v_rsq_f32_e32 v64, v52
	s_nop 0
	v_pk_mul_f32 v[50:51], v[50:51], v[64:65] op_sel_hi:[1,0]
	v_pk_mul_f32 v[48:49], v[48:49], v[64:65] op_sel_hi:[1,0]
	v_pk_mul_f32 v[46:47], v[46:47], v[64:65] op_sel_hi:[1,0]
	v_pk_mul_f32 v[44:45], v[44:45], v[64:65] op_sel_hi:[1,0]
	s_cbranch_vccnz .LBB0_424
	s_and_b64 vcc, exec, s[42:43]
	s_cbranch_vccnz .LBB0_421
	s_andn2_b64 vcc, exec, s[0:1]
	s_cbranch_vccnz .LBB0_418
	s_andn2_b64 vcc, exec, s[12:13]
	s_cbranch_vccnz .LBB0_415
	v_lshl_add_u64 v[52:53], s[64:65], 0, v[62:63]
	v_ashrrev_i32_e32 v55, 31, v2
	v_mov_b32_e32 v54, v2
	v_lshl_add_u64 v[68:69], v[54:55], 1, v[52:53]
	v_pk_mul_f32 v[54:55], v[50:51], s[88:89] op_sel_hi:[1,0]
	v_pk_mul_f32 v[52:53], v[48:49], s[88:89] op_sel_hi:[1,0]
	v_pk_mul_f32 v[58:59], v[46:47], s[88:89] op_sel_hi:[1,0]
	v_pk_mul_f32 v[56:57], v[44:45], s[88:89] op_sel_hi:[1,0]
	s_mov_b64 s[14:15], 0

.LBB0_442:
	s_nop 0
	v_add_u32_e32 v50, 0xb0, v182
	v_ashrrev_i32_e32 v51, 31, v50
	v_mad_i64_i32 v[44:45], s[14:15], v50, s95, 0
	s_and_b64 vcc, exec, s[44:45]
	v_lshlrev_b64 v[46:47], 9, v[50:51]
	s_mov_b64 s[14:15], -1
	v_fmamk_f32 v28, v215, 0x3a800000, v195
	v_rsq_f32_e32 v48, v28
	s_nop 0
	v_pk_mul_f32 v[18:19], v[18:19], v[48:49] op_sel_hi:[1,0]
	v_pk_mul_f32 v[16:17], v[16:17], v[48:49] op_sel_hi:[1,0]
	v_pk_mul_f32 v[14:15], v[14:15], v[48:49] op_sel_hi:[1,0]
	v_pk_mul_f32 v[12:13], v[12:13], v[48:49] op_sel_hi:[1,0]
	s_cbranch_vccnz .LBB0_456
	s_and_b64 vcc, exec, s[42:43]
	s_cbranch_vccnz .LBB0_453
	s_andn2_b64 vcc, exec, s[0:1]
	s_cbranch_vccnz .LBB0_450
	s_andn2_b64 vcc, exec, s[12:13]
	s_cbranch_vccnz .LBB0_447
	v_lshl_add_u64 v[28:29], s[64:65], 0, v[46:47]
	v_ashrrev_i32_e32 v31, 31, v2
	v_mov_b32_e32 v30, v2
	v_lshl_add_u64 v[52:53], v[30:31], 1, v[28:29]
	v_pk_mul_f32 v[30:31], v[18:19], s[88:89] op_sel_hi:[1,0]
	v_pk_mul_f32 v[28:29], v[16:17], s[88:89] op_sel_hi:[1,0]
	v_pk_mul_f32 v[34:35], v[14:15], s[88:89] op_sel_hi:[1,0]
	v_pk_mul_f32 v[32:33], v[12:13], s[88:89] op_sel_hi:[1,0]
	s_mov_b64 s[14:15], 0
